# attention row-sum of probabilities as pairwise tree instead of a 32-long dependent add chain
# speedup vs baseline: 1.0517x; 1.0031x over previous
.LBB0_229:
	v_add_f32_e32 v173, v173, v229
	v_add_f32_e32 v230, v230, v231
	v_add_f32_e32 v232, v232, v233
	v_add_f32_e32 v234, v234, v235
	v_add_f32_e32 v236, v236, v237
	v_add_f32_e32 v238, v238, v239
	v_add_f32_e32 v240, v240, v241
	v_add_f32_e32 v242, v242, v243
	v_add_f32_e32 v1, v1, v3
	v_add_f32_e32 v4, v4, v5
	v_add_f32_e32 v6, v6, v7
	v_add_f32_e32 v8, v8, v9
	v_add_f32_e32 v10, v10, v11
	v_add_f32_e32 v12, v12, v13
	v_add_f32_e32 v14, v14, v15
	v_add_f32_e32 v96, v96, v97
	v_add_f32_e32 v173, v173, v230
	v_add_f32_e32 v232, v232, v234
	v_add_f32_e32 v236, v236, v238
	v_add_f32_e32 v240, v240, v242
	v_add_f32_e32 v1, v1, v4
	v_add_f32_e32 v6, v6, v8
	v_add_f32_e32 v10, v10, v12
	v_add_f32_e32 v14, v14, v96
	v_add_f32_e32 v173, v173, v232
	v_add_f32_e32 v236, v236, v240
	v_add_f32_e32 v1, v1, v6
	v_add_f32_e32 v10, v10, v14
	v_add_f32_e32 v173, v173, v236
	v_add_f32_e32 v1, v1, v10
	v_add_f32_e32 v1, v1, v173
	v_add_f32_e32 v2, v2, v1
	s_mov_b64 s[64:65], 0
	s_andn2_b64 vcc, exec, s[62:63]
	s_cbranch_vccnz .LBB0_214
	s_branch .LBB0_233

.LBB0_1295:
	v_add_f32_e32 v173, v173, v231
	v_add_f32_e32 v232, v232, v233
	v_add_f32_e32 v234, v234, v235
	v_add_f32_e32 v236, v236, v237
	v_add_f32_e32 v238, v238, v239
	v_add_f32_e32 v241, v241, v242
	v_add_f32_e32 v243, v243, v244
	v_add_f32_e32 v245, v245, v246
	v_add_f32_e32 v1, v1, v3
	v_add_f32_e32 v4, v4, v5
	v_add_f32_e32 v6, v6, v7
	v_add_f32_e32 v8, v8, v9
	v_add_f32_e32 v10, v10, v11
	v_add_f32_e32 v12, v12, v13
	v_add_f32_e32 v14, v14, v15
	v_add_f32_e32 v96, v96, v97
	v_add_f32_e32 v173, v173, v232
	v_add_f32_e32 v234, v234, v236
	v_add_f32_e32 v238, v238, v241
	v_add_f32_e32 v243, v243, v245
	v_add_f32_e32 v1, v1, v4
	v_add_f32_e32 v6, v6, v8
	v_add_f32_e32 v10, v10, v12
	v_add_f32_e32 v14, v14, v96
	v_add_f32_e32 v173, v173, v234
	v_add_f32_e32 v238, v238, v243
	v_add_f32_e32 v1, v1, v6
	v_add_f32_e32 v10, v10, v14
	v_add_f32_e32 v173, v173, v238
	v_add_f32_e32 v1, v1, v10
	v_add_f32_e32 v1, v1, v173
	v_add_f32_e32 v2, v2, v1
	s_mov_b64 s[64:65], 0
	s_andn2_b64 vcc, exec, s[62:63]
	s_cbranch_vccnz .LBB0_1280
	s_branch .LBB0_1299
